# v24 + nt on the phase-0 normalized-activation (a0) stores
# baseline (speedup 1.0000x reference)
; __device__ __forceinline__ unsigned pk_bf16(float lo, float hi) { const f32x2 v = {lo, hi}; return __builtin_bit_cast(unsigned, __builtin_convertvector(v, b16x2)); }
;     __device__ __forceinline__ void row(int r, int col32, int fq, const f32x4& a00, const f32x4& a01, const f32x4& a10, const f32x4& a11) const { half(r, col32, fq, a00, a01); half(r, col32 + HALF, fq, a10, a11); }
;     __device__ __forceinline__ void row(int r, int col32, int fq, const f32x4& a00, const f32x4& a01, const f32x4& a10, const f32x4& a11) const { half(r, col32, fq, a00, a01); half(r, col32 + HALF, fq, a10, a11); }
;     __device__ __forceinline__ void row(int r, int col32, int fq, const f32x4& a00, const f32x4& a01, const f32x4& a10, const f32x4& a11) const { half(r, col32, fq, a00, a01); half(r, col32 + HALF, fq, a10, a11); }
; __device__ __forceinline__ void phase0(const Params& p) {
;     ...
;             for (int r = 0; r < 4; ++r) {
;                 const int row = row0 + r, b = row / TP, t = row - b * TP;
;                 float ss = 0.f;
; #pragma unroll
;                 for (int j = 0; j < 4; ++j) ss += (v[r][j][0] * v[r][j][0] + v[r][j][1] * v[r][j][1]) + (v[r][j][2] * v[r][j][2] + v[r][j][3] * v[r][j][3]);
;                 const float rs = t < T ? rsqrtf(wave_sum(ss) * (1.0f / D) + RMS_EPS) : 0.f;
;                 bf16_t* orow = (bf16_t*)(ws + O_A0) + (size_t)row * D;
; #pragma unroll
;                 for (int j = 0; j < 4; ++j) {
;                     u32x2 w; w.x = pk_bf16(v[r][j][0] * rs * g[j][0], v[r][j][1] * rs * g[j][1]); w.y = pk_bf16(v[r][j][2] * rs * g[j][2], v[r][j][3] * rs * g[j][3]);
;                     *(u32x2*)(orow + 4 * lane + 256 * j) = w;
;                 }
;             }
.LBB0_41:
	s_or_b64 exec, exec, s[4:5]
	v_ashrrev_i32_e32 v125, 31, v124
	s_waitcnt vmcnt(16)
	v_pk_mul_f32 v[64:65], v[64:65], v[150:151] op_sel_hi:[1,0]
	v_pk_mul_f32 v[66:67], v[66:67], v[150:151] op_sel_hi:[1,0]
	v_lshlrev_b64 v[166:167], 11, v[124:125]
	s_waitcnt vmcnt(0)
	v_pk_mul_f32 v[64:65], v[4:5], v[64:65]
	v_pk_mul_f32 v[66:67], v[6:7], v[66:67]
	v_lshl_add_u64 v[166:167], v[84:85], 0, v[166:167]
	v_cvt_pk_bf16_f32 v64, v64, v65
	v_cvt_pk_bf16_f32 v65, v66, v67
	v_pk_mul_f32 v[76:77], v[76:77], v[150:151] op_sel_hi:[1,0]
	v_pk_mul_f32 v[78:79], v[78:79], v[150:151] op_sel_hi:[1,0]
	v_pk_mul_f32 v[72:73], v[72:73], v[150:151] op_sel_hi:[1,0]
	v_pk_mul_f32 v[74:75], v[74:75], v[150:151] op_sel_hi:[1,0]
	v_pk_mul_f32 v[68:69], v[68:69], v[150:151] op_sel_hi:[1,0]
	v_pk_mul_f32 v[70:71], v[70:71], v[150:151] op_sel_hi:[1,0]
	global_store_dwordx2 v[166:167], v[64:65], off offset:1536 nt
	v_mul_i32_i24_e32 v64, 0x2080, v148
	v_pk_mul_f32 v[76:77], v[28:29], v[76:77]
	v_pk_mul_f32 v[78:79], v[30:31], v[78:79]
	v_pk_mul_f32 v[72:73], v[20:21], v[72:73]
	v_pk_mul_f32 v[74:75], v[22:23], v[74:75]
	v_pk_mul_f32 v[68:69], v[12:13], v[68:69]
	v_pk_mul_f32 v[70:71], v[14:15], v[70:71]
	v_sub_u32_e32 v64, v144, v64
	v_cvt_pk_bf16_f32 v76, v76, v77
	v_cvt_pk_bf16_f32 v77, v78, v79
	v_cvt_pk_bf16_f32 v72, v72, v73
	v_cvt_pk_bf16_f32 v73, v74, v75
	v_cvt_pk_bf16_f32 v68, v68, v69
	v_cvt_pk_bf16_f32 v69, v70, v71
	v_cmp_gt_i32_e32 vcc, s8, v64
	global_store_dwordx2 v[166:167], v[76:77], off nt
	global_store_dwordx2 v[166:167], v[72:73], off offset:512 nt
	global_store_dwordx2 v[166:167], v[68:69], off offset:1024 nt
	s_and_saveexec_b64 s[4:5], vcc
	s_cbranch_execz .LBB0_43
	v_pk_mul_f32 v[64:65], v[62:63], v[62:63]
	v_pk_mul_f32 v[66:67], v[60:61], v[60:61]
	v_mov_b32_e32 v69, v65
	v_mov_b32_e32 v68, v66
	v_pk_mov_b32 v[64:65], v[66:67], v[64:65] op_sel:[1,0]
	v_pk_mul_f32 v[66:67], v[58:59], v[58:59]
	v_pk_add_f32 v[64:65], v[64:65], v[68:69]
	v_pk_mul_f32 v[68:69], v[56:57], v[56:57]
	v_mov_b32_e32 v71, v67
	v_mov_b32_e32 v70, v68
	v_pk_mov_b32 v[66:67], v[68:69], v[66:67] op_sel:[1,0]
	v_mul_f32_e32 v68, v48, v48
	v_pk_add_f32 v[66:67], v[66:67], v[70:71]
	v_mul_f32_e32 v69, v49, v49
	v_pk_add_f32 v[64:65], v[64:65], v[64:65] op_sel:[0,1] op_sel_hi:[1,0]
	v_pk_add_f32 v[66:67], v[66:67], v[66:67] op_sel:[0,1] op_sel_hi:[1,0]
	v_mov_b32_e32 v65, v68
	v_mov_b32_e32 v67, v69
	v_pk_add_f32 v[64:65], v[64:65], v[66:67]
	v_mul_f32_e32 v66, v53, v53
	v_mul_f32_e32 v68, v55, v55
	v_mul_f32_e32 v70, v50, v50
	v_mul_f32_e32 v71, v51, v51
	v_pk_fma_f32 v[66:67], v[52:53], v[52:53], v[66:67] op_sel_hi:[1,1,0]
	v_pk_fma_f32 v[68:69], v[54:55], v[54:55], v[68:69] op_sel_hi:[1,1,0]
	v_mov_b32_e32 v67, v70
	v_mov_b32_e32 v69, v71
	v_pk_add_f32 v[66:67], v[66:67], v[68:69]
	s_nop 0
	v_pk_add_f32 v[64:65], v[64:65], v[66:67]
	v_xor_b32_e32 v66, 1, v139
	v_add_f32_e32 v64, v64, v65
	v_and_b32_e32 v65, 64, v139
	v_add_u32_e32 v65, 64, v65
	v_cmp_lt_i32_e32 vcc, v66, v65
	s_nop 1
	v_cndmask_b32_e32 v66, v139, v66, vcc
	v_lshlrev_b32_e32 v66, 2, v66
	ds_bpermute_b32 v66, v66, v64
	s_waitcnt lgkmcnt(0)
	v_add_f32_e32 v64, v64, v66
	v_xor_b32_e32 v66, 2, v139
	v_cmp_lt_i32_e32 vcc, v66, v65
	s_nop 1
	v_cndmask_b32_e32 v66, v139, v66, vcc
	v_lshlrev_b32_e32 v66, 2, v66
	ds_bpermute_b32 v66, v66, v64
	s_waitcnt lgkmcnt(0)
	v_add_f32_e32 v64, v64, v66
	v_xor_b32_e32 v66, 4, v139
	v_cmp_lt_i32_e32 vcc, v66, v65
	s_nop 1
	v_cndmask_b32_e32 v66, v139, v66, vcc
	v_lshlrev_b32_e32 v66, 2, v66
	ds_bpermute_b32 v66, v66, v64
	s_waitcnt lgkmcnt(0)
	v_add_f32_e32 v64, v64, v66
	v_xor_b32_e32 v66, 8, v139
	v_cmp_lt_i32_e32 vcc, v66, v65
	s_nop 1
	v_cndmask_b32_e32 v66, v139, v66, vcc
	v_lshlrev_b32_e32 v66, 2, v66
	ds_bpermute_b32 v66, v66, v64
	s_waitcnt lgkmcnt(0)
	v_add_f32_e32 v64, v64, v66
	v_xor_b32_e32 v66, 16, v139
	v_cmp_lt_i32_e32 vcc, v66, v65
	s_nop 1
	v_cndmask_b32_e32 v66, v139, v66, vcc
	v_lshlrev_b32_e32 v66, 2, v66
	ds_bpermute_b32 v66, v66, v64
	s_waitcnt lgkmcnt(0)
	v_add_f32_e32 v64, v64, v66
	v_xor_b32_e32 v66, 32, v139
	v_cmp_lt_i32_e32 vcc, v66, v65
	s_nop 1
	v_cndmask_b32_e32 v65, v139, v66, vcc
	v_lshlrev_b32_e32 v65, 2, v65
	ds_bpermute_b32 v65, v65, v64
	s_waitcnt lgkmcnt(0)
	v_add_f32_e32 v64, v64, v65
	v_fmamk_f32 v64, v64, 0x3a800000, v162
	v_mul_f32_e32 v65, 0x4b800000, v64
	v_cmp_gt_f32_e32 vcc, s9, v64
	s_nop 1
	v_cndmask_b32_e32 v64, v64, v65, vcc
	v_rsq_f32_e32 v64, v64
	s_nop 0
	v_mul_f32_e32 v65, 0x45800000, v64
	v_cndmask_b32_e32 v82, v64, v65, vcc
; __device__ __forceinline__ unsigned pk_bf16(float lo, float hi) { const f32x2 v = {lo, hi}; return __builtin_bit_cast(unsigned, __builtin_convertvector(v, b16x2)); }
;     __device__ __forceinline__ void row(int r, int col32, int fq, const f32x4& a00, const f32x4& a01, const f32x4& a10, const f32x4& a11) const { half(r, col32, fq, a00, a01); half(r, col32 + HALF, fq, a10, a11); }
;     __device__ __forceinline__ void row(int r, int col32, int fq, const f32x4& a00, const f32x4& a01, const f32x4& a10, const f32x4& a11) const { half(r, col32, fq, a00, a01); half(r, col32 + HALF, fq, a10, a11); }
;     __device__ __forceinline__ void row(int r, int col32, int fq, const f32x4& a00, const f32x4& a01, const f32x4& a10, const f32x4& a11) const { half(r, col32, fq, a00, a01); half(r, col32 + HALF, fq, a10, a11); }
; __device__ __forceinline__ void phase0(const Params& p) {
;     ...
;             for (int r = 0; r < 4; ++r) {
;                 const int row = row0 + r, b = row / TP, t = row - b * TP;
;                 float ss = 0.f;
; #pragma unroll
;                 for (int j = 0; j < 4; ++j) ss += (v[r][j][0] * v[r][j][0] + v[r][j][1] * v[r][j][1]) + (v[r][j][2] * v[r][j][2] + v[r][j][3] * v[r][j][3]);
;                 const float rs = t < T ? rsqrtf(wave_sum(ss) * (1.0f / D) + RMS_EPS) : 0.f;
;                 bf16_t* orow = (bf16_t*)(ws + O_A0) + (size_t)row * D;
; #pragma unroll
;                 for (int j = 0; j < 4; ++j) {
;                     u32x2 w; w.x = pk_bf16(v[r][j][0] * rs * g[j][0], v[r][j][1] * rs * g[j][1]); w.y = pk_bf16(v[r][j][2] * rs * g[j][2], v[r][j][3] * rs * g[j][3]);
;                     *(u32x2*)(orow + 4 * lane + 256 * j) = w;
;                 }
;             }
.LBB0_43:
	s_or_b64 exec, exec, s[4:5]
	v_ashrrev_i32_e32 v145, 31, v144
	v_pk_mul_f32 v[48:49], v[48:49], v[82:83] op_sel_hi:[1,0]
	v_pk_mul_f32 v[50:51], v[50:51], v[82:83] op_sel_hi:[1,0]
	v_lshlrev_b64 v[64:65], 11, v[144:145]
	v_pk_mul_f32 v[48:49], v[4:5], v[48:49]
	v_pk_mul_f32 v[50:51], v[6:7], v[50:51]
	v_lshl_add_u64 v[64:65], v[84:85], 0, v[64:65]
	v_cvt_pk_bf16_f32 v48, v48, v49
	v_cvt_pk_bf16_f32 v49, v50, v51
	v_pk_mul_f32 v[60:61], v[60:61], v[82:83] op_sel_hi:[1,0]
	v_pk_mul_f32 v[62:63], v[62:63], v[82:83] op_sel_hi:[1,0]
	v_pk_mul_f32 v[56:57], v[56:57], v[82:83] op_sel_hi:[1,0]
	v_pk_mul_f32 v[58:59], v[58:59], v[82:83] op_sel_hi:[1,0]
	v_pk_mul_f32 v[52:53], v[52:53], v[82:83] op_sel_hi:[1,0]
	v_pk_mul_f32 v[54:55], v[54:55], v[82:83] op_sel_hi:[1,0]
	global_store_dwordx2 v[64:65], v[48:49], off offset:1536 nt
	v_mul_i32_i24_e32 v48, 0x2080, v146
	v_pk_mul_f32 v[60:61], v[28:29], v[60:61]
	v_pk_mul_f32 v[62:63], v[30:31], v[62:63]
	v_pk_mul_f32 v[56:57], v[20:21], v[56:57]
	v_pk_mul_f32 v[58:59], v[22:23], v[58:59]
	v_pk_mul_f32 v[52:53], v[12:13], v[52:53]
	v_pk_mul_f32 v[54:55], v[14:15], v[54:55]
	v_sub_u32_e32 v48, v140, v48
	v_cvt_pk_bf16_f32 v60, v60, v61
	v_cvt_pk_bf16_f32 v61, v62, v63
	v_cvt_pk_bf16_f32 v56, v56, v57
	v_cvt_pk_bf16_f32 v57, v58, v59
	v_cvt_pk_bf16_f32 v52, v52, v53
	v_cvt_pk_bf16_f32 v53, v54, v55
	v_cmp_gt_i32_e32 vcc, s8, v48
	v_mov_b32_e32 v48, 0
	v_mov_b32_e32 v50, 0
	global_store_dwordx2 v[64:65], v[60:61], off nt
	global_store_dwordx2 v[64:65], v[56:57], off offset:512 nt
	global_store_dwordx2 v[64:65], v[52:53], off offset:1024 nt
	s_and_saveexec_b64 s[4:5], vcc
	s_cbranch_execz .LBB0_45
	v_pk_mul_f32 v[50:51], v[46:47], v[46:47]
	v_pk_mul_f32 v[52:53], v[44:45], v[44:45]
	v_mov_b32_e32 v55, v51
	v_mov_b32_e32 v54, v52
	v_pk_mov_b32 v[50:51], v[52:53], v[50:51] op_sel:[1,0]
	v_pk_mul_f32 v[52:53], v[42:43], v[42:43]
	v_pk_add_f32 v[50:51], v[50:51], v[54:55]
	v_pk_mul_f32 v[54:55], v[40:41], v[40:41]
	v_mov_b32_e32 v57, v53
	v_mov_b32_e32 v56, v54
	v_pk_mov_b32 v[52:53], v[54:55], v[52:53] op_sel:[1,0]
	v_mul_f32_e32 v49, v32, v32
	v_pk_add_f32 v[52:53], v[52:53], v[56:57]
	v_mul_f32_e32 v54, v33, v33
	v_pk_add_f32 v[50:51], v[50:51], v[50:51] op_sel:[0,1] op_sel_hi:[1,0]
	v_pk_add_f32 v[52:53], v[52:53], v[52:53] op_sel:[0,1] op_sel_hi:[1,0]
	v_mov_b32_e32 v51, v49
	v_mov_b32_e32 v53, v54
	v_pk_add_f32 v[50:51], v[50:51], v[52:53]
	v_mul_f32_e32 v52, v37, v37
	v_mul_f32_e32 v55, v34, v34
	v_pk_fma_f32 v[52:53], v[36:37], v[36:37], v[52:53] op_sel_hi:[1,1,0]
	v_mul_f32_e32 v54, v39, v39
	v_mul_f32_e32 v56, v35, v35
	v_mov_b32_e32 v53, v55
	v_pk_fma_f32 v[54:55], v[38:39], v[38:39], v[54:55] op_sel_hi:[1,1,0]
	s_nop 0
	v_mov_b32_e32 v55, v56
	v_pk_add_f32 v[52:53], v[52:53], v[54:55]
	s_nop 0
	v_pk_add_f32 v[50:51], v[50:51], v[52:53]
	s_nop 0
	v_add_f32_e32 v49, v50, v51
	v_and_b32_e32 v50, 64, v139
	v_add_u32_e32 v50, 64, v50
	v_xor_b32_e32 v51, 1, v139
	v_cmp_lt_i32_e32 vcc, v51, v50
	s_nop 1
	v_cndmask_b32_e32 v51, v139, v51, vcc
	v_lshlrev_b32_e32 v51, 2, v51
	ds_bpermute_b32 v51, v51, v49
	s_waitcnt lgkmcnt(0)
	v_add_f32_e32 v49, v49, v51
	v_xor_b32_e32 v51, 2, v139
	v_cmp_lt_i32_e32 vcc, v51, v50
	s_nop 1
	v_cndmask_b32_e32 v51, v139, v51, vcc
	v_lshlrev_b32_e32 v51, 2, v51
	ds_bpermute_b32 v51, v51, v49
	s_waitcnt lgkmcnt(0)
	v_add_f32_e32 v49, v49, v51
	v_xor_b32_e32 v51, 4, v139
	v_cmp_lt_i32_e32 vcc, v51, v50
	s_nop 1
	v_cndmask_b32_e32 v51, v139, v51, vcc
	v_lshlrev_b32_e32 v51, 2, v51
	ds_bpermute_b32 v51, v51, v49
	s_waitcnt lgkmcnt(0)
	v_add_f32_e32 v49, v49, v51
	v_xor_b32_e32 v51, 8, v139
	v_cmp_lt_i32_e32 vcc, v51, v50
	s_nop 1
	v_cndmask_b32_e32 v51, v139, v51, vcc
	v_lshlrev_b32_e32 v51, 2, v51
	ds_bpermute_b32 v51, v51, v49
	s_waitcnt lgkmcnt(0)
	v_add_f32_e32 v49, v49, v51
	v_xor_b32_e32 v51, 16, v139
	v_cmp_lt_i32_e32 vcc, v51, v50
	s_nop 1
	v_cndmask_b32_e32 v51, v139, v51, vcc
	v_lshlrev_b32_e32 v51, 2, v51
	ds_bpermute_b32 v51, v51, v49
	s_waitcnt lgkmcnt(0)
	v_add_f32_e32 v49, v49, v51
	v_xor_b32_e32 v51, 32, v139
	v_cmp_lt_i32_e32 vcc, v51, v50
	s_nop 1
	v_cndmask_b32_e32 v50, v139, v51, vcc
	v_lshlrev_b32_e32 v50, 2, v50
	ds_bpermute_b32 v50, v50, v49
	s_waitcnt lgkmcnt(0)
	v_add_f32_e32 v49, v49, v50
	v_fmamk_f32 v49, v49, 0x3a800000, v162
	v_mul_f32_e32 v50, 0x4b800000, v49
	v_cmp_gt_f32_e32 vcc, s9, v49
	s_nop 1
	v_cndmask_b32_e32 v49, v49, v50, vcc
	v_rsq_f32_e32 v49, v49
	s_nop 0
	v_mul_f32_e32 v50, 0x45800000, v49
	v_cndmask_b32_e32 v50, v49, v50, vcc
; __device__ __forceinline__ unsigned pk_bf16(float lo, float hi) { const f32x2 v = {lo, hi}; return __builtin_bit_cast(unsigned, __builtin_convertvector(v, b16x2)); }
;     __device__ __forceinline__ void row(int r, int col32, int fq, const f32x4& a00, const f32x4& a01, const f32x4& a10, const f32x4& a11) const { half(r, col32, fq, a00, a01); half(r, col32 + HALF, fq, a10, a11); }
;     __device__ __forceinline__ void row(int r, int col32, int fq, const f32x4& a00, const f32x4& a01, const f32x4& a10, const f32x4& a11) const { half(r, col32, fq, a00, a01); half(r, col32 + HALF, fq, a10, a11); }
;     __device__ __forceinline__ void row(int r, int col32, int fq, const f32x4& a00, const f32x4& a01, const f32x4& a10, const f32x4& a11) const { half(r, col32, fq, a00, a01); half(r, col32 + HALF, fq, a10, a11); }
; __device__ __forceinline__ void phase0(const Params& p) {
;     ...
;             for (int r = 0; r < 4; ++r) {
;                 const int row = row0 + r, b = row / TP, t = row - b * TP;
;                 float ss = 0.f;
; #pragma unroll
;                 for (int j = 0; j < 4; ++j) ss += (v[r][j][0] * v[r][j][0] + v[r][j][1] * v[r][j][1]) + (v[r][j][2] * v[r][j][2] + v[r][j][3] * v[r][j][3]);
;                 const float rs = t < T ? rsqrtf(wave_sum(ss) * (1.0f / D) + RMS_EPS) : 0.f;
;                 bf16_t* orow = (bf16_t*)(ws + O_A0) + (size_t)row * D;
; #pragma unroll
;                 for (int j = 0; j < 4; ++j) {
;                     u32x2 w; w.x = pk_bf16(v[r][j][0] * rs * g[j][0], v[r][j][1] * rs * g[j][1]); w.y = pk_bf16(v[r][j][2] * rs * g[j][2], v[r][j][3] * rs * g[j][3]);
;                     *(u32x2*)(orow + 4 * lane + 256 * j) = w;
;                 }
;             }
.LBB0_45:
	s_or_b64 exec, exec, s[4:5]
	v_ashrrev_i32_e32 v141, 31, v140
	v_pk_mul_f32 v[32:33], v[32:33], v[50:51] op_sel_hi:[1,0]
	v_pk_mul_f32 v[34:35], v[34:35], v[50:51] op_sel_hi:[1,0]
	v_lshlrev_b64 v[52:53], 11, v[140:141]
	v_pk_mul_f32 v[32:33], v[4:5], v[32:33]
	v_pk_mul_f32 v[34:35], v[6:7], v[34:35]
	v_lshl_add_u64 v[52:53], v[84:85], 0, v[52:53]
	v_cvt_pk_bf16_f32 v32, v32, v33
	v_cvt_pk_bf16_f32 v33, v34, v35
	v_pk_mul_f32 v[44:45], v[44:45], v[50:51] op_sel_hi:[1,0]
	v_pk_mul_f32 v[46:47], v[46:47], v[50:51] op_sel_hi:[1,0]
	v_pk_mul_f32 v[40:41], v[40:41], v[50:51] op_sel_hi:[1,0]
	v_pk_mul_f32 v[42:43], v[42:43], v[50:51] op_sel_hi:[1,0]
	v_pk_mul_f32 v[36:37], v[36:37], v[50:51] op_sel_hi:[1,0]
	v_pk_mul_f32 v[38:39], v[38:39], v[50:51] op_sel_hi:[1,0]
	global_store_dwordx2 v[52:53], v[32:33], off offset:1536 nt
	v_mul_i32_i24_e32 v32, 0x2080, v142
	v_pk_mul_f32 v[44:45], v[28:29], v[44:45]
	v_pk_mul_f32 v[46:47], v[30:31], v[46:47]
	v_pk_mul_f32 v[40:41], v[20:21], v[40:41]
	v_pk_mul_f32 v[42:43], v[22:23], v[42:43]
	v_pk_mul_f32 v[36:37], v[12:13], v[36:37]
	v_pk_mul_f32 v[38:39], v[14:15], v[38:39]
	v_sub_u32_e32 v32, v138, v32
	v_cvt_pk_bf16_f32 v44, v44, v45
	v_cvt_pk_bf16_f32 v45, v46, v47
	v_cvt_pk_bf16_f32 v40, v40, v41
	v_cvt_pk_bf16_f32 v41, v42, v43
	v_cvt_pk_bf16_f32 v36, v36, v37
	v_cvt_pk_bf16_f32 v37, v38, v39
	v_cmp_gt_i32_e32 vcc, s8, v32
	global_store_dwordx2 v[52:53], v[44:45], off nt
	global_store_dwordx2 v[52:53], v[40:41], off offset:512 nt
	global_store_dwordx2 v[52:53], v[36:37], off offset:1024 nt
	s_and_saveexec_b64 s[4:5], vcc
	s_cbranch_execz .LBB0_47
	v_pk_mul_f32 v[32:33], v[26:27], v[26:27]
	v_pk_mul_f32 v[34:35], v[24:25], v[24:25]
	v_mov_b32_e32 v37, v33
	v_mov_b32_e32 v36, v34
	v_pk_mov_b32 v[32:33], v[34:35], v[32:33] op_sel:[1,0]
	v_pk_mul_f32 v[34:35], v[18:19], v[18:19]
	v_pk_add_f32 v[32:33], v[32:33], v[36:37]
	v_pk_mul_f32 v[36:37], v[16:17], v[16:17]
	v_mov_b32_e32 v39, v35
	v_mov_b32_e32 v38, v36
	v_pk_mov_b32 v[34:35], v[36:37], v[34:35] op_sel:[1,0]
	v_mul_f32_e32 v36, v0, v0
	v_pk_add_f32 v[34:35], v[34:35], v[38:39]
	v_mul_f32_e32 v37, v1, v1
	v_pk_add_f32 v[32:33], v[32:33], v[32:33] op_sel:[0,1] op_sel_hi:[1,0]
	v_pk_add_f32 v[34:35], v[34:35], v[34:35] op_sel:[0,1] op_sel_hi:[1,0]
	v_mov_b32_e32 v33, v36
	v_mov_b32_e32 v35, v37
	v_pk_add_f32 v[32:33], v[32:33], v[34:35]
	v_mul_f32_e32 v34, v9, v9
	v_mul_f32_e32 v36, v11, v11
	v_mul_f32_e32 v38, v2, v2
	v_mul_f32_e32 v39, v3, v3
	v_pk_fma_f32 v[34:35], v[8:9], v[8:9], v[34:35] op_sel_hi:[1,1,0]
	v_pk_fma_f32 v[36:37], v[10:11], v[10:11], v[36:37] op_sel_hi:[1,1,0]
	v_mov_b32_e32 v35, v38
	v_mov_b32_e32 v37, v39
	v_pk_add_f32 v[34:35], v[34:35], v[36:37]
	s_nop 0
	v_pk_add_f32 v[32:33], v[32:33], v[34:35]
	v_xor_b32_e32 v34, 1, v139
	v_add_f32_e32 v32, v32, v33
	v_and_b32_e32 v33, 64, v139
	v_add_u32_e32 v33, 64, v33
	v_cmp_lt_i32_e32 vcc, v34, v33
	s_nop 1
	v_cndmask_b32_e32 v34, v139, v34, vcc
	v_lshlrev_b32_e32 v34, 2, v34
	ds_bpermute_b32 v34, v34, v32
	s_waitcnt lgkmcnt(0)
	v_add_f32_e32 v32, v32, v34
	v_xor_b32_e32 v34, 2, v139
	v_cmp_lt_i32_e32 vcc, v34, v33
	s_nop 1
	v_cndmask_b32_e32 v34, v139, v34, vcc
	v_lshlrev_b32_e32 v34, 2, v34
	ds_bpermute_b32 v34, v34, v32
	s_waitcnt lgkmcnt(0)
	v_add_f32_e32 v32, v32, v34
	v_xor_b32_e32 v34, 4, v139
	v_cmp_lt_i32_e32 vcc, v34, v33
	s_nop 1
	v_cndmask_b32_e32 v34, v139, v34, vcc
	v_lshlrev_b32_e32 v34, 2, v34
	ds_bpermute_b32 v34, v34, v32
	s_waitcnt lgkmcnt(0)
	v_add_f32_e32 v32, v32, v34
	v_xor_b32_e32 v34, 8, v139
	v_cmp_lt_i32_e32 vcc, v34, v33
	s_nop 1
	v_cndmask_b32_e32 v34, v139, v34, vcc
	v_lshlrev_b32_e32 v34, 2, v34
	ds_bpermute_b32 v34, v34, v32
	s_waitcnt lgkmcnt(0)
	v_add_f32_e32 v32, v32, v34
	v_xor_b32_e32 v34, 16, v139
	v_cmp_lt_i32_e32 vcc, v34, v33
	s_nop 1
	v_cndmask_b32_e32 v34, v139, v34, vcc
	v_lshlrev_b32_e32 v34, 2, v34
	ds_bpermute_b32 v34, v34, v32
	s_waitcnt lgkmcnt(0)
	v_add_f32_e32 v32, v32, v34
	v_xor_b32_e32 v34, 32, v139
	v_cmp_lt_i32_e32 vcc, v34, v33
	s_nop 1
	v_cndmask_b32_e32 v33, v139, v34, vcc
	v_lshlrev_b32_e32 v33, 2, v33
	ds_bpermute_b32 v33, v33, v32
	s_waitcnt lgkmcnt(0)
	v_add_f32_e32 v32, v32, v33
	v_fmamk_f32 v32, v32, 0x3a800000, v162
	v_mul_f32_e32 v33, 0x4b800000, v32
	v_cmp_gt_f32_e32 vcc, s9, v32
	s_nop 1
	v_cndmask_b32_e32 v32, v32, v33, vcc
	v_rsq_f32_e32 v32, v32
	s_nop 0
	v_mul_f32_e32 v33, 0x45800000, v32
	v_cndmask_b32_e32 v48, v32, v33, vcc
.LBB0_47:
	s_or_b64 exec, exec, s[4:5]
	v_ashrrev_i32_e32 v139, 31, v138
	v_pk_mul_f32 v[24:25], v[24:25], v[48:49] op_sel_hi:[1,0]
	v_pk_mul_f32 v[26:27], v[26:27], v[48:49] op_sel_hi:[1,0]
	v_pk_mul_f32 v[16:17], v[16:17], v[48:49] op_sel_hi:[1,0]
	v_pk_mul_f32 v[18:19], v[18:19], v[48:49] op_sel_hi:[1,0]
	v_pk_mul_f32 v[8:9], v[8:9], v[48:49] op_sel_hi:[1,0]
	v_pk_mul_f32 v[10:11], v[10:11], v[48:49] op_sel_hi:[1,0]
	v_pk_mul_f32 v[0:1], v[0:1], v[48:49] op_sel_hi:[1,0]
	v_pk_mul_f32 v[2:3], v[2:3], v[48:49] op_sel_hi:[1,0]
	v_lshlrev_b64 v[32:33], 11, v[138:139]
	v_pk_mul_f32 v[24:25], v[28:29], v[24:25]
	v_pk_mul_f32 v[26:27], v[30:31], v[26:27]
	v_pk_mul_f32 v[16:17], v[20:21], v[16:17]
	v_pk_mul_f32 v[18:19], v[22:23], v[18:19]
	v_pk_mul_f32 v[8:9], v[12:13], v[8:9]
	v_pk_mul_f32 v[10:11], v[14:15], v[10:11]
	v_pk_mul_f32 v[0:1], v[4:5], v[0:1]
	v_pk_mul_f32 v[2:3], v[6:7], v[2:3]
	v_lshl_add_u64 v[32:33], v[84:85], 0, v[32:33]
	v_cvt_pk_bf16_f32 v24, v24, v25
	v_cvt_pk_bf16_f32 v25, v26, v27
	v_cvt_pk_bf16_f32 v16, v16, v17
	v_cvt_pk_bf16_f32 v17, v18, v19
	v_cvt_pk_bf16_f32 v8, v8, v9
	v_cvt_pk_bf16_f32 v9, v10, v11
	v_cvt_pk_bf16_f32 v0, v0, v1
	v_cvt_pk_bf16_f32 v1, v2, v3
	s_mov_b64 s[4:5], 0
	global_store_dwordx2 v[32:33], v[24:25], off nt
	global_store_dwordx2 v[32:33], v[16:17], off offset:512 nt
	global_store_dwordx2 v[32:33], v[8:9], off offset:1024 nt
	global_store_dwordx2 v[32:33], v[0:1], off offset:1536 nt
